# D epilogue inputs (row sum-of-squares words and conv weights) prefetched at unit start by two LDS-DMA loads per wave into the unused LDS tail; the epilogue reads them from LDS, so it starts without a
# speedup vs baseline: 1.0063x; 1.0063x over previous
.LBB0_124:
	s_ashr_i32 s79, s78, 31
	s_lshl_b64 s[10:11], s[78:79], 19
	s_add_u32 s80, s54, s10
	v_cmp_lt_i64_e32 vcc, s[72:73], v[178:179]
	s_addc_u32 s81, s55, s11
	s_and_b64 s[10:11], vcc, exec
	s_cselect_b32 s1, s81, s87
	s_cselect_b32 s10, s80, s86
	s_ashr_i32 s77, s76, 31
	s_lshl_b64 s[36:37], s[76:77], 19
	s_add_u32 s72, s66, s36
	s_addc_u32 s73, s59, s37
	s_and_b64 s[36:37], vcc, exec
	s_cselect_b32 s11, s73, s83
	s_cselect_b32 s25, s72, s82
	s_add_u32 s86, s86, 0x40080
	s_addc_u32 s87, s87, 0
	s_add_u32 s33, s82, 0x100
	v_mov_b32_e32 v0, 0
	s_addc_u32 s36, s83, 0
	s_mov_b32 s37, -2
	v_mov_b32_e32 v1, v0
	v_mov_b32_e32 v2, v0
	v_mov_b32_e32 v3, v0
	v_mov_b32_e32 v32, v0
	v_mov_b32_e32 v33, v0
	v_mov_b32_e32 v34, v0
	v_mov_b32_e32 v35, v0
	v_mov_b32_e32 v4, v0
	v_mov_b32_e32 v5, v0
	v_mov_b32_e32 v6, v0
	v_mov_b32_e32 v7, v0
	v_mov_b32_e32 v36, v0
	v_mov_b32_e32 v37, v0
	v_mov_b32_e32 v38, v0
	v_mov_b32_e32 v39, v0
	v_mov_b32_e32 v8, v0
	v_mov_b32_e32 v9, v0
	v_mov_b32_e32 v10, v0
	v_mov_b32_e32 v11, v0
	v_mov_b32_e32 v40, v0
	v_mov_b32_e32 v41, v0
	v_mov_b32_e32 v42, v0
	v_mov_b32_e32 v43, v0
	v_mov_b32_e32 v12, v0
	v_mov_b32_e32 v13, v0
	v_mov_b32_e32 v14, v0
	v_mov_b32_e32 v15, v0
	v_mov_b32_e32 v44, v0
	v_mov_b32_e32 v45, v0
	v_mov_b32_e32 v46, v0
	v_mov_b32_e32 v47, v0
	v_mov_b32_e32 v24, v0
	v_mov_b32_e32 v25, v0
	v_mov_b32_e32 v26, v0
	v_mov_b32_e32 v27, v0
	v_mov_b32_e32 v52, v0
	v_mov_b32_e32 v53, v0
	v_mov_b32_e32 v54, v0
	v_mov_b32_e32 v55, v0
	v_mov_b32_e32 v16, v0
	v_mov_b32_e32 v17, v0
	v_mov_b32_e32 v18, v0
	v_mov_b32_e32 v19, v0
	v_mov_b32_e32 v56, v0
	v_mov_b32_e32 v57, v0
	v_mov_b32_e32 v58, v0
	v_mov_b32_e32 v59, v0
	v_mov_b32_e32 v28, v0
	v_mov_b32_e32 v29, v0
	v_mov_b32_e32 v30, v0
	v_mov_b32_e32 v31, v0
	v_mov_b32_e32 v60, v0
	v_mov_b32_e32 v61, v0
	v_mov_b32_e32 v62, v0
	v_mov_b32_e32 v63, v0
	v_mov_b32_e32 v20, v0
	v_mov_b32_e32 v21, v0
	v_mov_b32_e32 v22, v0
	v_mov_b32_e32 v23, v0
	v_mov_b32_e32 v48, v0
	v_mov_b32_e32 v49, v0
	v_mov_b32_e32 v50, v0
	v_mov_b32_e32 v51, v0
	v_mov_b32_e32 v96, v0
	v_mov_b32_e32 v97, v0
	v_mov_b32_e32 v98, v0
	v_mov_b32_e32 v99, v0
	v_mov_b32_e32 v128, v0
	v_mov_b32_e32 v129, v0
	v_mov_b32_e32 v130, v0
	v_mov_b32_e32 v131, v0
	v_mov_b32_e32 v100, v0
	v_mov_b32_e32 v101, v0
	v_mov_b32_e32 v102, v0
	v_mov_b32_e32 v103, v0
	v_mov_b32_e32 v132, v0
	v_mov_b32_e32 v133, v0
	v_mov_b32_e32 v134, v0
	v_mov_b32_e32 v135, v0
	v_mov_b32_e32 v104, v0
	v_mov_b32_e32 v105, v0
	v_mov_b32_e32 v106, v0
	v_mov_b32_e32 v107, v0
	v_mov_b32_e32 v136, v0
	v_mov_b32_e32 v137, v0
	v_mov_b32_e32 v138, v0
	v_mov_b32_e32 v139, v0
	v_mov_b32_e32 v108, v0
	v_mov_b32_e32 v109, v0
	v_mov_b32_e32 v110, v0
	v_mov_b32_e32 v111, v0
	v_mov_b32_e32 v140, v0
	v_mov_b32_e32 v141, v0
	v_mov_b32_e32 v142, v0
	v_mov_b32_e32 v143, v0
	v_mov_b32_e32 v120, v0
	v_mov_b32_e32 v121, v0
	v_mov_b32_e32 v122, v0
	v_mov_b32_e32 v123, v0
	v_mov_b32_e32 v150, v0
	v_mov_b32_e32 v151, v0
	v_mov_b32_e32 v152, v0
	v_mov_b32_e32 v153, v0
	v_mov_b32_e32 v112, v0
	v_mov_b32_e32 v113, v0
	v_mov_b32_e32 v114, v0
	v_mov_b32_e32 v115, v0
	v_mov_b32_e32 v154, v0
	v_mov_b32_e32 v155, v0
	v_mov_b32_e32 v156, v0
	v_mov_b32_e32 v157, v0
	v_mov_b32_e32 v124, v0
	v_mov_b32_e32 v125, v0
	v_mov_b32_e32 v126, v0
	v_mov_b32_e32 v127, v0
	v_mov_b32_e32 v158, v0
	v_mov_b32_e32 v159, v0
	v_mov_b32_e32 v160, v0
	v_mov_b32_e32 v161, v0
	v_mov_b32_e32 v116, v0
	v_mov_b32_e32 v117, v0
	v_mov_b32_e32 v118, v0
	v_mov_b32_e32 v119, v0
	v_mov_b32_e32 v146, v0
	v_mov_b32_e32 v147, v0
	v_mov_b32_e32 v148, v0
	v_mov_b32_e32 v149, v0
	s_lshr_b32 s27, s28, 6
	s_lshl_b32 s56, s27, 11
	s_add_i32 s56, s56, 0x20800
	v_lshrrev_b32_e32 v168, 3, v214
	v_and_b32_e32 v169, 7, v214
	v_lshlrev_b32_e32 v176, 4, v168
	v_and_b32_e32 v176, 48, v176
	v_bfe_u32 v177, v214, 5, 1
	v_lshl_or_b32 v176, v177, 7, v176
	s_lshl_b32 s57, s84, 8
	v_readlane_b32 s58, v254, 61
	s_add_i32 s57, s57, s58
	v_add_u32_e32 v176, s57, v176
	v_lshlrev_b32_e32 v176, 3, v176
	v_lshl_add_u32 v176, v169, 4, v176
	v_mov_b32_e32 v177, 0
	v_lshl_add_u64 v[176:177], s[48:49], 0, v[176:177]
	s_mov_b32 m0, s56
	v_and_b32_e32 v168, 3, v168
	global_load_lds_dwordx4 v[176:177], off
	s_and_b32 s57, s27, 3
	s_lshl_b32 s57, s57, 7
	s_lshl_b32 s58, s0, 9
	s_add_i32 s57, s57, s58
	v_cmp_eq_u32_e32 vcc, 3, v168
	v_lshl_add_u32 v242, v169, 4, s57
	v_mov_b32_e32 v243, 0
	v_mul_u32_u24_e32 v240, 0x2c00, v168
	v_add_u32_e32 v240, v242, v240
	v_mov_b32_e32 v241, 0
	v_lshl_add_u64 v[240:241], s[68:69], 0, v[240:241]
	v_lshl_add_u64 v[242:243], s[70:71], 0, v[242:243]
	v_cndmask_b32_e32 v240, v240, v242, vcc
	v_cndmask_b32_e32 v241, v241, v243, vcc
	s_add_i32 m0, s56, 0x400
	s_nop 0
	global_load_lds_dwordx4 v[240:241], off
.LBB0_125:
	s_add_u32 s27, s86, 0xfffc0080
	s_addc_u32 s56, s87, -1
	s_add_i32 s57, 0, 0x10000
	v_add_u32_e32 v76, s57, v217
	ds_read_b128 v[64:67], v76
	ds_read_b128 v[68:71], v76 offset:1024
	ds_read_b128 v[72:75], v76 offset:2048
	ds_read_b128 v[76:79], v76 offset:3072
	s_cmp_eq_u32 s37, 12
	s_cselect_b32 vcc_hi, s1, s56
	s_cselect_b32 vcc_lo, s10, s27
	s_cselect_b32 s83, s11, s36
	s_cselect_b32 s82, s25, s33
	v_lshl_add_u64 v[168:169], s[86:87], 0, v[164:165]
	s_add_i32 m0, s75, 0xc000
	ds_read_b128 v[80:83], v220
	ds_read_b128 v[84:87], v220 offset:1024
	ds_read_b128 v[88:91], v220 offset:2048
	ds_read_b128 v[92:95], v220 offset:3072
	ds_read_b128 v[188:191], v220 offset:4096
	ds_read_b128 v[192:195], v220 offset:5120
	ds_read_b128 v[196:199], v220 offset:6144
	ds_read_b128 v[200:203], v220 offset:7168
	global_load_lds_dwordx4 v[168:169], off
	v_lshl_add_u64 v[168:169], s[86:87], 0, v[166:167]
	s_add_i32 m0, s75, 0xe000
	s_nop 0
	global_load_lds_dwordx4 v[168:169], off
	s_waitcnt lgkmcnt(8)
	s_barrier
	s_waitcnt lgkmcnt(0)
	s_setprio 1
	s_waitcnt lgkmcnt(0)
	v_mfma_f32_16x16x32_bf16 v[146:149], v[64:67], v[80:83], v[146:149]
	v_mfma_f32_16x16x32_bf16 v[116:119], v[72:75], v[80:83], v[116:119]
	v_mfma_f32_16x16x32_bf16 v[158:161], v[64:67], v[88:91], v[158:161]
	v_mfma_f32_16x16x32_bf16 v[124:127], v[72:75], v[88:91], v[124:127]
	v_mfma_f32_16x16x32_bf16 v[154:157], v[64:67], v[188:191], v[154:157]
	v_mfma_f32_16x16x32_bf16 v[112:115], v[72:75], v[188:191], v[112:115]
	v_mfma_f32_16x16x32_bf16 v[150:153], v[64:67], v[196:199], v[150:153]
	v_mfma_f32_16x16x32_bf16 v[120:123], v[72:75], v[196:199], v[120:123]
	v_mfma_f32_16x16x32_bf16 v[146:149], v[68:71], v[84:87], v[146:149]
	v_mfma_f32_16x16x32_bf16 v[116:119], v[76:79], v[84:87], v[116:119]
	v_mfma_f32_16x16x32_bf16 v[158:161], v[68:71], v[92:95], v[158:161]
	v_mfma_f32_16x16x32_bf16 v[124:127], v[76:79], v[92:95], v[124:127]
	v_mfma_f32_16x16x32_bf16 v[154:157], v[68:71], v[192:195], v[154:157]
	v_mfma_f32_16x16x32_bf16 v[112:115], v[76:79], v[192:195], v[112:115]
	v_mfma_f32_16x16x32_bf16 v[150:153], v[68:71], v[200:203], v[150:153]
	v_mfma_f32_16x16x32_bf16 v[120:123], v[76:79], v[200:203], v[120:123]
	s_setprio 0
	s_barrier
	s_add_i32 s27, 0, 0x14000
	v_add_u32_e32 v168, s27, v217
	s_add_i32 s56, s57, s74
	ds_read_b128 v[204:207], v168
	ds_read_b128 v[222:225], v168 offset:1024
	ds_read_b128 v[228:231], v168 offset:2048
	ds_read_b128 v[232:235], v168 offset:3072
	v_lshl_add_u64 v[168:169], s[82:83], 0, v[144:145]
	s_mov_b32 m0, s56
	v_lshl_add_u64 v[176:177], s[82:83], 0, v[162:163]
	global_load_lds_dwordx4 v[168:169], off
	s_add_i32 m0, s56, 0x2000
	s_nop 0
	global_load_lds_dwordx4 v[176:177], off
	s_barrier
	s_waitcnt lgkmcnt(0)
	s_setprio 1
	s_waitcnt lgkmcnt(0)
	v_mfma_f32_16x16x32_bf16 v[140:143], v[204:207], v[80:83], v[140:143]
	v_mfma_f32_16x16x32_bf16 v[80:83], v[228:231], v[80:83], v[108:111]
	v_mfma_f32_16x16x32_bf16 v[140:143], v[222:225], v[84:87], v[140:143]
	v_mfma_f32_16x16x32_bf16 v[80:83], v[232:235], v[84:87], v[80:83]
	v_mfma_f32_16x16x32_bf16 v[84:87], v[204:207], v[88:91], v[136:139]
	v_mfma_f32_16x16x32_bf16 v[88:91], v[228:231], v[88:91], v[104:107]
	v_mfma_f32_16x16x32_bf16 v[100:103], v[228:231], v[188:191], v[100:103]
	v_mfma_f32_16x16x32_bf16 v[104:107], v[204:207], v[196:199], v[128:131]
	v_mfma_f32_16x16x32_bf16 v[96:99], v[228:231], v[196:199], v[96:99]
	v_mfma_f32_16x16x32_bf16 v[84:87], v[222:225], v[92:95], v[84:87]
	v_mfma_f32_16x16x32_bf16 v[88:91], v[232:235], v[92:95], v[88:91]
	v_mfma_f32_16x16x32_bf16 v[92:95], v[204:207], v[188:191], v[132:135]
	v_mfma_f32_16x16x32_bf16 v[100:103], v[232:235], v[192:195], v[100:103]
	v_mfma_f32_16x16x32_bf16 v[128:131], v[222:225], v[200:203], v[104:107]
	v_mfma_f32_16x16x32_bf16 v[96:99], v[232:235], v[200:203], v[96:99]
	v_mfma_f32_16x16x32_bf16 v[92:95], v[222:225], v[192:195], v[92:95]
	s_setprio 0
	s_mov_b32 m0, s75
	v_lshl_add_u64 v[240:241], vcc, 0, v[144:145]
	s_barrier
	ds_read_b128 v[104:107], v220 offset:16384
	ds_read_b128 v[108:111], v220 offset:17408
	ds_read_b128 v[132:135], v220 offset:18432
	ds_read_b128 v[136:139], v220 offset:19456
	ds_read_b128 v[188:191], v220 offset:20480
	ds_read_b128 v[192:195], v220 offset:21504
	ds_read_b128 v[196:199], v220 offset:22528
	ds_read_b128 v[200:203], v220 offset:23552
	global_load_lds_dwordx4 v[240:241], off
	v_lshl_add_u64 v[242:243], vcc, 0, v[162:163]
	s_mov_b32 m0, s85
	s_nop 0
	global_load_lds_dwordx4 v[242:243], off
	s_barrier
	s_waitcnt lgkmcnt(0)
	s_setprio 1
	s_waitcnt lgkmcnt(0)
	v_mfma_f32_16x16x32_bf16 v[48:51], v[64:67], v[104:107], v[48:51]
	v_mfma_f32_16x16x32_bf16 v[20:23], v[72:75], v[104:107], v[20:23]
	v_mfma_f32_16x16x32_bf16 v[60:63], v[64:67], v[132:135], v[60:63]
	v_mfma_f32_16x16x32_bf16 v[28:31], v[72:75], v[132:135], v[28:31]
	v_mfma_f32_16x16x32_bf16 v[56:59], v[64:67], v[188:191], v[56:59]
	v_mfma_f32_16x16x32_bf16 v[16:19], v[72:75], v[188:191], v[16:19]
	v_mfma_f32_16x16x32_bf16 v[52:55], v[64:67], v[196:199], v[52:55]
	v_mfma_f32_16x16x32_bf16 v[24:27], v[72:75], v[196:199], v[24:27]
	v_mfma_f32_16x16x32_bf16 v[48:51], v[68:71], v[108:111], v[48:51]
	v_mfma_f32_16x16x32_bf16 v[20:23], v[76:79], v[108:111], v[20:23]
	v_mfma_f32_16x16x32_bf16 v[60:63], v[68:71], v[136:139], v[60:63]
	v_mfma_f32_16x16x32_bf16 v[28:31], v[76:79], v[136:139], v[28:31]
	v_mfma_f32_16x16x32_bf16 v[56:59], v[68:71], v[192:195], v[56:59]
	v_mfma_f32_16x16x32_bf16 v[16:19], v[76:79], v[192:195], v[16:19]
	v_mfma_f32_16x16x32_bf16 v[52:55], v[68:71], v[200:203], v[52:55]
	v_mfma_f32_16x16x32_bf16 v[24:27], v[76:79], v[200:203], v[24:27]
	s_setprio 0
	s_barrier
	s_add_u32 s56, s82, 0x40000
	s_addc_u32 s57, s83, 0
	s_add_i32 s27, s27, s74
	v_lshl_add_u64 v[64:65], s[56:57], 0, v[144:145]
	s_mov_b32 m0, s27
	s_nop 0
	global_load_lds_dwordx4 v[64:65], off
	v_lshl_add_u64 v[64:65], s[56:57], 0, v[162:163]
	s_add_i32 m0, s27, 0x2000
	s_nop 0
	global_load_lds_dwordx4 v[64:65], off
	s_waitcnt vmcnt(6)
	s_barrier
	s_setprio 1
	v_mfma_f32_16x16x32_bf16 v[44:47], v[204:207], v[104:107], v[44:47]
	v_mfma_f32_16x16x32_bf16 v[12:15], v[228:231], v[104:107], v[12:15]
	v_mfma_f32_16x16x32_bf16 v[40:43], v[204:207], v[132:135], v[40:43]
	v_mfma_f32_16x16x32_bf16 v[8:11], v[228:231], v[132:135], v[8:11]
	v_mfma_f32_16x16x32_bf16 v[36:39], v[204:207], v[188:191], v[36:39]
	v_mfma_f32_16x16x32_bf16 v[4:7], v[228:231], v[188:191], v[4:7]
	v_mfma_f32_16x16x32_bf16 v[32:35], v[204:207], v[196:199], v[32:35]
	v_mfma_f32_16x16x32_bf16 v[0:3], v[228:231], v[196:199], v[0:3]
	v_mfma_f32_16x16x32_bf16 v[44:47], v[222:225], v[108:111], v[44:47]
	v_mfma_f32_16x16x32_bf16 v[12:15], v[232:235], v[108:111], v[12:15]
	v_mfma_f32_16x16x32_bf16 v[40:43], v[222:225], v[136:139], v[40:43]
	v_mfma_f32_16x16x32_bf16 v[8:11], v[232:235], v[136:139], v[8:11]
	v_mfma_f32_16x16x32_bf16 v[36:39], v[222:225], v[192:195], v[36:39]
	v_mfma_f32_16x16x32_bf16 v[4:7], v[232:235], v[192:195], v[4:7]
	v_mfma_f32_16x16x32_bf16 v[32:35], v[222:225], v[200:203], v[32:35]
	v_mfma_f32_16x16x32_bf16 v[0:3], v[232:235], v[200:203], v[0:3]
	s_setprio 0
	s_add_i32 s27, 0, 0x18000
	v_add_u32_e32 v76, s27, v217
	s_barrier
	ds_read_b128 v[64:67], v76
	ds_read_b128 v[68:71], v76 offset:1024
	ds_read_b128 v[72:75], v76 offset:2048
	ds_read_b128 v[76:79], v76 offset:3072
	s_add_u32 s56, vcc_lo, 0x40000
	s_addc_u32 s57, vcc_hi, 0
	s_mov_b32 m0, s98
	v_lshl_add_u64 v[136:137], s[56:57], 0, v[144:145]
	ds_read_b128 v[104:107], v220 offset:32768
	ds_read_b128 v[108:111], v220 offset:33792
	ds_read_b128 v[132:135], v220 offset:34816
	ds_read_b128 v[188:191], v220 offset:35840
	ds_read_b128 v[192:195], v220 offset:36864
	ds_read_b128 v[196:199], v220 offset:37888
	ds_read_b128 v[200:203], v220 offset:38912
	ds_read_b128 v[204:207], v220 offset:39936
	global_load_lds_dwordx4 v[136:137], off
	v_lshl_add_u64 v[136:137], s[56:57], 0, v[162:163]
	s_mov_b32 m0, s29
	s_nop 0
	global_load_lds_dwordx4 v[136:137], off
	s_waitcnt lgkmcnt(8)
	s_barrier
	s_waitcnt lgkmcnt(0)
	s_setprio 1
	s_waitcnt lgkmcnt(0)
	v_mfma_f32_16x16x32_bf16 v[136:139], v[64:67], v[104:107], v[146:149]
	v_mfma_f32_16x16x32_bf16 v[146:149], v[68:71], v[108:111], v[136:139]
	v_mfma_f32_16x16x32_bf16 v[136:139], v[64:67], v[132:135], v[158:161]
	v_mfma_f32_16x16x32_bf16 v[158:161], v[68:71], v[188:191], v[136:139]
	v_mfma_f32_16x16x32_bf16 v[136:139], v[64:67], v[192:195], v[154:157]
	v_mfma_f32_16x16x32_bf16 v[116:119], v[72:75], v[104:107], v[116:119]
	v_mfma_f32_16x16x32_bf16 v[124:127], v[72:75], v[132:135], v[124:127]
	v_mfma_f32_16x16x32_bf16 v[154:157], v[68:71], v[196:199], v[136:139]
	v_mfma_f32_16x16x32_bf16 v[112:115], v[72:75], v[192:195], v[112:115]
	v_mfma_f32_16x16x32_bf16 v[136:139], v[64:67], v[200:203], v[150:153]
	v_mfma_f32_16x16x32_bf16 v[120:123], v[72:75], v[200:203], v[120:123]
	v_mfma_f32_16x16x32_bf16 v[116:119], v[76:79], v[108:111], v[116:119]
	v_mfma_f32_16x16x32_bf16 v[124:127], v[76:79], v[188:191], v[124:127]
	v_mfma_f32_16x16x32_bf16 v[112:115], v[76:79], v[196:199], v[112:115]
	v_mfma_f32_16x16x32_bf16 v[150:153], v[68:71], v[204:207], v[136:139]
	v_mfma_f32_16x16x32_bf16 v[120:123], v[76:79], v[204:207], v[120:123]
	s_setprio 0
	s_barrier
	s_add_i32 s58, 0, 0x1c000
	v_add_u32_e32 v136, s58, v217
	s_add_i32 s27, s27, s74
	ds_read_b128 v[222:225], v136
	ds_read_b128 v[228:231], v136 offset:1024
	ds_read_b128 v[232:235], v136 offset:2048
	ds_read_b128 v[236:239], v136 offset:3072
	v_lshl_add_u64 v[136:137], v[168:169], 0, s[18:19]
	s_mov_b32 m0, s27
	s_nop 0
	global_load_lds_dwordx4 v[136:137], off
	v_lshl_add_u64 v[136:137], v[176:177], 0, s[18:19]
	s_add_i32 m0, s27, 0x2000
	s_nop 0
	global_load_lds_dwordx4 v[136:137], off
	s_barrier
	s_waitcnt lgkmcnt(0)
	s_setprio 1
	s_waitcnt lgkmcnt(0)
	v_mfma_f32_16x16x32_bf16 v[136:139], v[222:225], v[104:107], v[140:143]
	v_mfma_f32_16x16x32_bf16 v[80:83], v[232:235], v[104:107], v[80:83]
	v_mfma_f32_16x16x32_bf16 v[140:143], v[228:231], v[108:111], v[136:139]
	v_mfma_f32_16x16x32_bf16 v[108:111], v[236:239], v[108:111], v[80:83]
	v_mfma_f32_16x16x32_bf16 v[80:83], v[222:225], v[132:135], v[84:87]
	v_mfma_f32_16x16x32_bf16 v[136:139], v[228:231], v[188:191], v[80:83]
	v_mfma_f32_16x16x32_bf16 v[80:83], v[232:235], v[132:135], v[88:91]
	v_mfma_f32_16x16x32_bf16 v[104:107], v[236:239], v[188:191], v[80:83]
	v_mfma_f32_16x16x32_bf16 v[80:83], v[222:225], v[192:195], v[92:95]
	v_mfma_f32_16x16x32_bf16 v[132:135], v[228:231], v[196:199], v[80:83]
	v_mfma_f32_16x16x32_bf16 v[80:83], v[232:235], v[192:195], v[100:103]
	v_mfma_f32_16x16x32_bf16 v[100:103], v[236:239], v[196:199], v[80:83]
	v_mfma_f32_16x16x32_bf16 v[80:83], v[222:225], v[200:203], v[128:131]
	v_mfma_f32_16x16x32_bf16 v[128:131], v[228:231], v[204:207], v[80:83]
	v_mfma_f32_16x16x32_bf16 v[80:83], v[232:235], v[200:203], v[96:99]
	v_mfma_f32_16x16x32_bf16 v[96:99], v[236:239], v[204:207], v[80:83]
	s_setprio 0
	s_mov_b32 m0, s31
	v_lshl_add_u64 v[168:169], v[240:241], 0, s[18:19]
	s_barrier
	s_nop 2
	ds_read_b128 v[80:83], v220 offset:49152
	ds_read_b128 v[84:87], v220 offset:50176
	ds_read_b128 v[88:91], v220 offset:51200
	ds_read_b128 v[92:95], v220 offset:52224
	ds_read_b128 v[188:191], v220 offset:53248
	ds_read_b128 v[192:195], v220 offset:54272
	ds_read_b128 v[196:199], v220 offset:55296
	ds_read_b128 v[200:203], v220 offset:56320
	global_load_lds_dwordx4 v[168:169], off
	v_lshl_add_u64 v[168:169], v[242:243], 0, s[18:19]
	s_mov_b32 m0, s34
	s_nop 0
	global_load_lds_dwordx4 v[168:169], off
	s_barrier
	s_waitcnt lgkmcnt(0)
	s_setprio 1
	s_waitcnt lgkmcnt(0)
	v_mfma_f32_16x16x32_bf16 v[48:51], v[64:67], v[80:83], v[48:51]
	v_mfma_f32_16x16x32_bf16 v[20:23], v[72:75], v[80:83], v[20:23]
	v_mfma_f32_16x16x32_bf16 v[60:63], v[64:67], v[88:91], v[60:63]
	v_mfma_f32_16x16x32_bf16 v[28:31], v[72:75], v[88:91], v[28:31]
	v_mfma_f32_16x16x32_bf16 v[56:59], v[64:67], v[188:191], v[56:59]
	v_mfma_f32_16x16x32_bf16 v[16:19], v[72:75], v[188:191], v[16:19]
	v_mfma_f32_16x16x32_bf16 v[52:55], v[64:67], v[196:199], v[52:55]
	v_mfma_f32_16x16x32_bf16 v[24:27], v[72:75], v[196:199], v[24:27]
	v_mfma_f32_16x16x32_bf16 v[48:51], v[68:71], v[84:87], v[48:51]
	v_mfma_f32_16x16x32_bf16 v[20:23], v[76:79], v[84:87], v[20:23]
	v_mfma_f32_16x16x32_bf16 v[60:63], v[68:71], v[92:95], v[60:63]
	v_mfma_f32_16x16x32_bf16 v[28:31], v[76:79], v[92:95], v[28:31]
	v_mfma_f32_16x16x32_bf16 v[56:59], v[68:71], v[192:195], v[56:59]
	v_mfma_f32_16x16x32_bf16 v[16:19], v[76:79], v[192:195], v[16:19]
	v_mfma_f32_16x16x32_bf16 v[52:55], v[68:71], v[200:203], v[52:55]
	v_mfma_f32_16x16x32_bf16 v[24:27], v[76:79], v[200:203], v[24:27]
	s_setprio 0
	s_barrier
	s_add_u32 s56, s82, 0x40080
	s_addc_u32 s57, s83, 0
	s_add_i32 s27, s58, s74
	v_lshl_add_u64 v[64:65], s[56:57], 0, v[144:145]
	s_mov_b32 m0, s27
	s_nop 0
	global_load_lds_dwordx4 v[64:65], off
	v_lshl_add_u64 v[64:65], s[56:57], 0, v[162:163]
	s_add_i32 m0, s27, 0x2000
	s_nop 0
	global_load_lds_dwordx4 v[64:65], off
	s_waitcnt vmcnt(6)
	s_barrier
	s_setprio 1
	v_mfma_f32_16x16x32_bf16 v[44:47], v[222:225], v[80:83], v[44:47]
	v_mfma_f32_16x16x32_bf16 v[12:15], v[232:235], v[80:83], v[12:15]
	v_mfma_f32_16x16x32_bf16 v[40:43], v[222:225], v[88:91], v[40:43]
	v_mfma_f32_16x16x32_bf16 v[8:11], v[232:235], v[88:91], v[8:11]
	v_mfma_f32_16x16x32_bf16 v[36:39], v[222:225], v[188:191], v[36:39]
	v_mfma_f32_16x16x32_bf16 v[4:7], v[232:235], v[188:191], v[4:7]
	v_mfma_f32_16x16x32_bf16 v[32:35], v[222:225], v[196:199], v[32:35]
	v_mfma_f32_16x16x32_bf16 v[0:3], v[232:235], v[196:199], v[0:3]
	v_mfma_f32_16x16x32_bf16 v[44:47], v[228:231], v[84:87], v[44:47]
	v_mfma_f32_16x16x32_bf16 v[12:15], v[236:239], v[84:87], v[12:15]
	v_mfma_f32_16x16x32_bf16 v[40:43], v[228:231], v[92:95], v[40:43]
	v_mfma_f32_16x16x32_bf16 v[8:11], v[236:239], v[92:95], v[8:11]
	v_mfma_f32_16x16x32_bf16 v[36:39], v[228:231], v[192:195], v[36:39]
	v_mfma_f32_16x16x32_bf16 v[4:7], v[236:239], v[192:195], v[4:7]
	v_mfma_f32_16x16x32_bf16 v[32:35], v[228:231], v[200:203], v[32:35]
	v_mfma_f32_16x16x32_bf16 v[0:3], v[236:239], v[200:203], v[0:3]
	s_setprio 0
	s_add_i32 s37, s37, 2
	s_add_u32 s86, s86, 0x100
	s_addc_u32 s87, s87, 0
	s_add_u32 s33, s33, 0x100
	s_addc_u32 s36, s36, 0
	s_cmp_gt_u32 s37, 13
	s_barrier
	s_cbranch_scc0 .LBB0_125
	s_lshl_b32 s1, s84, 8
	v_readlane_b32 s10, v254, 61
	s_add_i32 s1, s1, s10
	v_or_b32_e32 v198, s1, v216
	v_ashrrev_i32_e32 v199, 31, v198
	s_add_i32 s10, s1, 0x80
	v_or_b32_e32 v168, s10, v216
	v_ashrrev_i32_e32 v169, 31, v168
	v_lshl_or_b32 v188, s0, 7, v219
	v_ashrrev_i32_e32 v189, 31, v188
	v_lshlrev_b64 v[190:191], 2, v[188:189]
	s_lshr_b32 s10, s28, 6
	s_lshl_b32 s10, s10, 11
	s_add_i32 s10, s10, 0x20800
	v_lshl_add_u32 v170, v216, 3, s10
	v_and_b32_e32 v171, 24, v219
	s_addk_i32 s10, 0x400
	v_lshl_add_u32 v171, v171, 2, s10
	ds_read_b64 v[176:177], v170
	ds_read_b64 v[202:203], v170 offset:128
	ds_read_b64 v[206:207], v170 offset:256
	ds_read_b64 v[222:223], v170 offset:384
	ds_read_b64 v[200:201], v170 offset:512
	ds_read_b64 v[196:197], v170 offset:640
	ds_read_b64 v[194:195], v170 offset:768
	ds_read_b64 v[192:193], v170 offset:896
	ds_read_b128 v[80:83], v171
	ds_read_b128 v[64:67], v171 offset:16
	ds_read_b128 v[88:91], v171 offset:128
	ds_read_b128 v[72:75], v171 offset:144
	ds_read_b128 v[92:95], v171 offset:256
	ds_read_b128 v[76:79], v171 offset:272
	ds_read_b128 v[84:87], v171 offset:384
	ds_read_b128 v[68:71], v171 offset:400
	s_ashr_i32 s11, s1, 5
	s_movk_i32 s10, 0xb00
	s_movk_i32 s20, 0x1600
	v_cmp_eq_u32_e64 s[36:37], 15, v216
	s_waitcnt lgkmcnt(8)
	v_ffbh_u32_e32 v224, v177
	v_ffbh_u32_e32 v225, v203
	v_ffbh_u32_e32 v226, v207
	v_ffbh_u32_e32 v227, v223
	v_ffbh_u32_e32 v228, v201
	v_ffbh_u32_e32 v229, v197
	v_ffbh_u32_e32 v230, v195
	v_ffbh_u32_e32 v231, v193
	v_min_u32_e32 v224, 32, v224
	v_min_u32_e32 v225, 32, v225
	v_min_u32_e32 v226, 32, v226
	v_min_u32_e32 v227, 32, v227
	v_min_u32_e32 v228, 32, v228
	v_min_u32_e32 v229, 32, v229
	v_min_u32_e32 v230, 32, v230
	v_min_u32_e32 v231, 32, v231
	v_lshlrev_b64 v[176:177], v224, v[176:177]
	v_lshlrev_b64 v[202:203], v225, v[202:203]
	v_lshlrev_b64 v[206:207], v226, v[206:207]
	v_lshlrev_b64 v[222:223], v227, v[222:223]
	v_lshlrev_b64 v[200:201], v228, v[200:201]
	v_lshlrev_b64 v[196:197], v229, v[196:197]
	v_lshlrev_b64 v[194:195], v230, v[194:195]
	v_lshlrev_b64 v[192:193], v231, v[192:193]
	v_min_u32_e32 v176, 1, v176
	v_min_u32_e32 v202, 1, v202
	v_min_u32_e32 v206, 1, v206
	v_min_u32_e32 v222, 1, v222
	v_min_u32_e32 v200, 1, v200
	v_min_u32_e32 v196, 1, v196
	v_min_u32_e32 v194, 1, v194
	v_min_u32_e32 v192, 1, v192
	v_or_b32_e32 v176, v177, v176
	v_or_b32_e32 v202, v203, v202
	v_or_b32_e32 v206, v207, v206
	v_or_b32_e32 v222, v223, v222
	v_or_b32_e32 v200, v201, v200
	v_or_b32_e32 v196, v197, v196
	v_or_b32_e32 v194, v195, v194
	v_or_b32_e32 v192, v193, v192
	v_cvt_f32_u32_e32 v176, v176
	v_cvt_f32_u32_e32 v202, v202
	v_cvt_f32_u32_e32 v206, v206
	v_cvt_f32_u32_e32 v222, v222
	v_cvt_f32_u32_e32 v200, v200
	v_cvt_f32_u32_e32 v196, v196
	v_cvt_f32_u32_e32 v194, v194
	v_cvt_f32_u32_e32 v192, v192
	v_sub_u32_e32 v224, 32, v224
	v_sub_u32_e32 v225, 32, v225
	v_sub_u32_e32 v226, 32, v226
	v_sub_u32_e32 v227, 32, v227
	v_sub_u32_e32 v228, 32, v228
	v_sub_u32_e32 v229, 32, v229
	v_sub_u32_e32 v230, 32, v230
	v_sub_u32_e32 v231, 32, v231
	v_ldexp_f32 v176, v176, v224
	v_ldexp_f32 v202, v202, v225
	v_ldexp_f32 v206, v206, v226
	v_ldexp_f32 v222, v222, v227
	v_ldexp_f32 v200, v200, v228
	v_ldexp_f32 v196, v196, v229
	v_ldexp_f32 v194, v194, v230
	v_ldexp_f32 v192, v192, v231
	v_mul_f32_e32 v176, 0x35800000, v176
	v_mul_f32_e32 v202, 0x35800000, v202
	v_mul_f32_e32 v206, 0x35800000, v206
	v_mul_f32_e32 v222, 0x35800000, v222
	v_mul_f32_e32 v200, 0x35800000, v200
	v_mul_f32_e32 v196, 0x35800000, v196
	v_mul_f32_e32 v194, 0x35800000, v194
	v_mul_f32_e32 v192, 0x35800000, v192
	v_fmamk_f32 v176, v176, 0x3a800000, v210
	v_fmamk_f32 v202, v202, 0x3a800000, v210
	v_fmamk_f32 v206, v206, 0x3a800000, v210
	v_fmamk_f32 v222, v222, 0x3a800000, v210
	v_fmamk_f32 v200, v200, 0x3a800000, v210
	v_fmamk_f32 v196, v196, 0x3a800000, v210
	v_fmamk_f32 v194, v194, 0x3a800000, v210
	v_fmamk_f32 v192, v192, 0x3a800000, v210
	v_rsq_f32_e32 v244, v176
	v_rsq_f32_e32 v245, v202
	v_rsq_f32_e32 v246, v206
	v_rsq_f32_e32 v247, v222
	v_rsq_f32_e32 v248, v200
	v_rsq_f32_e32 v249, v196
	v_rsq_f32_e32 v250, v194
	v_rsq_f32_e32 v251, v192
	s_waitcnt lgkmcnt(0)
	v_mul_f32_e32 v146, v146, v244
	v_mul_f32_e32 v158, v158, v245
	v_mul_f32_e32 v154, v154, v246
	v_mul_f32_e32 v150, v150, v247
	v_mul_f32_e32 v147, v147, v244
	v_mul_f32_e32 v159, v159, v245
	v_mul_f32_e32 v155, v155, v246
	v_mul_f32_e32 v151, v151, v247
	v_cndmask_b32_e64 v221, v146, 0, s[36:37]
	v_cndmask_b32_e64 v225, v146, 0, s[44:45]
	v_cndmask_b32_e64 v222, v158, v146, s[36:37]
	v_cndmask_b32_e64 v226, v158, v146, s[44:45]
	v_cndmask_b32_e64 v223, v154, v158, s[36:37]
	v_cndmask_b32_e64 v227, v154, v158, s[44:45]
	v_cndmask_b32_e64 v224, v150, v154, s[36:37]
	v_cndmask_b32_e64 v228, v150, v154, s[44:45]
	v_cndmask_b32_e64 v232, v147, 0, s[36:37]
	v_cndmask_b32_e64 v236, v147, 0, s[44:45]
	v_cndmask_b32_e64 v233, v159, v147, s[36:37]
	v_cndmask_b32_e64 v237, v159, v147, s[44:45]
	v_cndmask_b32_e64 v234, v155, v159, s[36:37]
	v_cndmask_b32_e64 v238, v155, v159, s[44:45]
	v_cndmask_b32_e64 v235, v151, v155, s[36:37]
	v_cndmask_b32_e64 v239, v151, v155, s[44:45]
	v_fma_f32 v200, v92, v146, v84
	v_fma_f32 v229, v92, v158, v84
	v_fma_f32 v230, v92, v154, v84
	v_fma_f32 v231, v92, v150, v84
	v_fma_f32 v201, v93, v147, v85
	v_fma_f32 v196, v93, v159, v85
	v_fma_f32 v197, v93, v155, v85
	v_fma_f32 v176, v93, v151, v85
	v_fmac_f32_dpp v200, v221, v88 row_ror:1 row_mask:0xf bank_mask:0xf
	v_fmac_f32_dpp v229, v222, v88 row_ror:1 row_mask:0xf bank_mask:0xf
	v_fmac_f32_dpp v230, v223, v88 row_ror:1 row_mask:0xf bank_mask:0xf
	v_fmac_f32_dpp v231, v224, v88 row_ror:1 row_mask:0xf bank_mask:0xf
	v_fmac_f32_dpp v201, v232, v89 row_ror:1 row_mask:0xf bank_mask:0xf
	v_fmac_f32_dpp v196, v233, v89 row_ror:1 row_mask:0xf bank_mask:0xf
	v_fmac_f32_dpp v197, v234, v89 row_ror:1 row_mask:0xf bank_mask:0xf
	v_fmac_f32_dpp v176, v235, v89 row_ror:1 row_mask:0xf bank_mask:0xf
	v_fmac_f32_dpp v200, v225, v80 row_ror:2 row_mask:0xf bank_mask:0xf
	v_fmac_f32_dpp v229, v226, v80 row_ror:2 row_mask:0xf bank_mask:0xf
	v_fmac_f32_dpp v230, v227, v80 row_ror:2 row_mask:0xf bank_mask:0xf
	v_fmac_f32_dpp v231, v228, v80 row_ror:2 row_mask:0xf bank_mask:0xf
	v_fmac_f32_dpp v201, v236, v81 row_ror:2 row_mask:0xf bank_mask:0xf
	v_fmac_f32_dpp v196, v237, v81 row_ror:2 row_mask:0xf bank_mask:0xf
	v_fmac_f32_dpp v197, v238, v81 row_ror:2 row_mask:0xf bank_mask:0xf
	v_fmac_f32_dpp v176, v239, v81 row_ror:2 row_mask:0xf bank_mask:0xf
	v_mul_f32_e32 v221, 0xbfb8aa3b, v200
	v_mul_f32_e32 v222, 0xbfb8aa3b, v229
	v_mul_f32_e32 v223, 0xbfb8aa3b, v230
	v_mul_f32_e32 v224, 0xbfb8aa3b, v231
	v_mul_f32_e32 v232, 0xbfb8aa3b, v201
	v_mul_f32_e32 v233, 0xbfb8aa3b, v196
	v_mul_f32_e32 v234, 0xbfb8aa3b, v197
	v_mul_f32_e32 v235, 0xbfb8aa3b, v176
	v_exp_f32_e32 v221, v221
	v_exp_f32_e32 v222, v222
	v_exp_f32_e32 v223, v223
	v_exp_f32_e32 v224, v224
	v_exp_f32_e32 v232, v232
	v_exp_f32_e32 v233, v233
	v_exp_f32_e32 v234, v234
	v_exp_f32_e32 v235, v235
	v_add_f32_e32 v221, 1.0, v221
	v_add_f32_e32 v222, 1.0, v222
	v_add_f32_e32 v223, 1.0, v223
	v_add_f32_e32 v224, 1.0, v224
	v_add_f32_e32 v232, 1.0, v232
	v_add_f32_e32 v233, 1.0, v233
	v_add_f32_e32 v234, 1.0, v234
	v_add_f32_e32 v235, 1.0, v235
	v_rcp_f32_e32 v221, v221
	v_rcp_f32_e32 v222, v222
	v_rcp_f32_e32 v223, v223
	v_rcp_f32_e32 v224, v224
	v_rcp_f32_e32 v232, v232
	v_rcp_f32_e32 v233, v233
	v_rcp_f32_e32 v234, v234
	v_rcp_f32_e32 v235, v235
	v_mul_f32_e32 v221, v200, v221
	v_mul_f32_e32 v222, v229, v222
	v_mul_f32_e32 v223, v230, v223
	v_mul_f32_e32 v224, v231, v224
	v_mul_f32_e32 v232, v201, v232
	v_mul_f32_e32 v233, v196, v233
	v_mul_f32_e32 v234, v197, v234
	v_mul_f32_e32 v235, v176, v235
	v_mul_f32_e32 v192, v140, v244
	v_mul_f32_e32 v136, v136, v245
	v_mul_f32_e32 v132, v132, v246
	v_mul_f32_e32 v128, v128, v247
	v_mul_f32_e32 v193, v141, v244
	v_mul_f32_e32 v137, v137, v245
	v_mul_f32_e32 v133, v133, v246
	v_mul_f32_e32 v129, v129, v247
	v_mul_f32_e32 v140, v221, v192
	v_mul_f32_e32 v136, v222, v136
	v_mul_f32_e32 v132, v223, v132
	v_mul_f32_e32 v128, v224, v128
	v_mul_f32_e32 v141, v232, v193
	v_mul_f32_e32 v137, v233, v137
	v_mul_f32_e32 v133, v234, v133
	v_mul_f32_e32 v129, v235, v129
	v_mul_f32_e32 v148, v148, v244
	v_mul_f32_e32 v160, v160, v245
	v_mul_f32_e32 v156, v156, v246
	v_mul_f32_e32 v152, v152, v247
	v_mul_f32_e32 v149, v149, v244
	v_mul_f32_e32 v161, v161, v245
	v_mul_f32_e32 v157, v157, v246
	v_mul_f32_e32 v153, v153, v247
	v_cndmask_b32_e64 v221, v148, 0, s[36:37]
	v_cndmask_b32_e64 v225, v148, 0, s[44:45]
	v_cndmask_b32_e64 v222, v160, v148, s[36:37]
	v_cndmask_b32_e64 v226, v160, v148, s[44:45]
	v_cndmask_b32_e64 v223, v156, v160, s[36:37]
	v_cndmask_b32_e64 v227, v156, v160, s[44:45]
	v_cndmask_b32_e64 v224, v152, v156, s[36:37]
	v_cndmask_b32_e64 v228, v152, v156, s[44:45]
	v_cndmask_b32_e64 v232, v149, 0, s[36:37]
	v_cndmask_b32_e64 v236, v149, 0, s[44:45]
	v_cndmask_b32_e64 v233, v161, v149, s[36:37]
	v_cndmask_b32_e64 v237, v161, v149, s[44:45]
	v_cndmask_b32_e64 v234, v157, v161, s[36:37]
	v_cndmask_b32_e64 v238, v157, v161, s[44:45]
	v_cndmask_b32_e64 v235, v153, v157, s[36:37]
	v_cndmask_b32_e64 v239, v153, v157, s[44:45]
	v_fma_f32 v202, v94, v148, v86
	v_fma_f32 v229, v94, v160, v86
	v_fma_f32 v230, v94, v156, v86
	v_fma_f32 v231, v94, v152, v86
	v_fma_f32 v203, v95, v149, v87
	v_fma_f32 v196, v95, v161, v87
	v_fma_f32 v197, v95, v157, v87
	v_fma_f32 v176, v95, v153, v87
	v_fmac_f32_dpp v202, v221, v90 row_ror:1 row_mask:0xf bank_mask:0xf
	v_fmac_f32_dpp v229, v222, v90 row_ror:1 row_mask:0xf bank_mask:0xf
	v_fmac_f32_dpp v230, v223, v90 row_ror:1 row_mask:0xf bank_mask:0xf
	v_fmac_f32_dpp v231, v224, v90 row_ror:1 row_mask:0xf bank_mask:0xf
	v_fmac_f32_dpp v203, v232, v91 row_ror:1 row_mask:0xf bank_mask:0xf
	v_fmac_f32_dpp v196, v233, v91 row_ror:1 row_mask:0xf bank_mask:0xf
	v_fmac_f32_dpp v197, v234, v91 row_ror:1 row_mask:0xf bank_mask:0xf
	v_fmac_f32_dpp v176, v235, v91 row_ror:1 row_mask:0xf bank_mask:0xf
	v_fmac_f32_dpp v202, v225, v82 row_ror:2 row_mask:0xf bank_mask:0xf
	v_fmac_f32_dpp v229, v226, v82 row_ror:2 row_mask:0xf bank_mask:0xf
	v_fmac_f32_dpp v230, v227, v82 row_ror:2 row_mask:0xf bank_mask:0xf
	v_fmac_f32_dpp v231, v228, v82 row_ror:2 row_mask:0xf bank_mask:0xf
	v_fmac_f32_dpp v203, v236, v83 row_ror:2 row_mask:0xf bank_mask:0xf
	v_fmac_f32_dpp v196, v237, v83 row_ror:2 row_mask:0xf bank_mask:0xf
	v_fmac_f32_dpp v197, v238, v83 row_ror:2 row_mask:0xf bank_mask:0xf
	v_fmac_f32_dpp v176, v239, v83 row_ror:2 row_mask:0xf bank_mask:0xf
	v_mul_f32_e32 v221, 0xbfb8aa3b, v202
	v_mul_f32_e32 v222, 0xbfb8aa3b, v229
	v_mul_f32_e32 v223, 0xbfb8aa3b, v230
	v_mul_f32_e32 v224, 0xbfb8aa3b, v231
	v_mul_f32_e32 v232, 0xbfb8aa3b, v203
	v_mul_f32_e32 v233, 0xbfb8aa3b, v196
	v_mul_f32_e32 v234, 0xbfb8aa3b, v197
	v_mul_f32_e32 v235, 0xbfb8aa3b, v176
	v_exp_f32_e32 v221, v221
	v_exp_f32_e32 v222, v222
	v_exp_f32_e32 v223, v223
	v_exp_f32_e32 v224, v224
	v_exp_f32_e32 v232, v232
	v_exp_f32_e32 v233, v233
	v_exp_f32_e32 v234, v234
	v_exp_f32_e32 v235, v235
	v_add_f32_e32 v221, 1.0, v221
	v_add_f32_e32 v222, 1.0, v222
	v_add_f32_e32 v223, 1.0, v223
	v_add_f32_e32 v224, 1.0, v224
	v_add_f32_e32 v232, 1.0, v232
	v_add_f32_e32 v233, 1.0, v233
	v_add_f32_e32 v234, 1.0, v234
	v_add_f32_e32 v235, 1.0, v235
	v_rcp_f32_e32 v221, v221
	v_rcp_f32_e32 v222, v222
	v_rcp_f32_e32 v223, v223
	v_rcp_f32_e32 v224, v224
	v_rcp_f32_e32 v232, v232
	v_rcp_f32_e32 v233, v233
	v_rcp_f32_e32 v234, v234
	v_rcp_f32_e32 v235, v235
	v_mul_f32_e32 v221, v202, v221
	v_mul_f32_e32 v222, v229, v222
	v_mul_f32_e32 v223, v230, v223
	v_mul_f32_e32 v224, v231, v224
	v_mul_f32_e32 v232, v203, v232
	v_mul_f32_e32 v233, v196, v233
	v_mul_f32_e32 v234, v197, v234
	v_mul_f32_e32 v235, v176, v235
	v_mul_f32_e32 v194, v142, v244
	v_mul_f32_e32 v138, v138, v245
	v_mul_f32_e32 v134, v134, v246
	v_mul_f32_e32 v130, v130, v247
	v_mul_f32_e32 v195, v143, v244
	v_mul_f32_e32 v139, v139, v245
	v_mul_f32_e32 v135, v135, v246
	v_mul_f32_e32 v131, v131, v247
	v_mul_f32_e32 v142, v221, v194
	v_mul_f32_e32 v138, v222, v138
	v_mul_f32_e32 v134, v223, v134
	v_mul_f32_e32 v130, v224, v130
	v_mul_f32_e32 v143, v232, v195
	v_mul_f32_e32 v139, v233, v139
	v_mul_f32_e32 v135, v234, v135
	v_mul_f32_e32 v131, v235, v131
	v_mul_f32_e32 v116, v116, v244
	v_mul_f32_e32 v124, v124, v245
	v_mul_f32_e32 v112, v112, v246
	v_mul_f32_e32 v120, v120, v247
	v_mul_f32_e32 v117, v117, v244
	v_mul_f32_e32 v125, v125, v245
	v_mul_f32_e32 v113, v113, v246
	v_mul_f32_e32 v121, v121, v247
	v_cndmask_b32_e64 v221, v116, 0, s[36:37]
	v_cndmask_b32_e64 v225, v116, 0, s[44:45]
	v_cndmask_b32_e64 v222, v124, v116, s[36:37]
	v_cndmask_b32_e64 v226, v124, v116, s[44:45]
	v_cndmask_b32_e64 v223, v112, v124, s[36:37]
	v_cndmask_b32_e64 v227, v112, v124, s[44:45]
	v_cndmask_b32_e64 v224, v120, v112, s[36:37]
	v_cndmask_b32_e64 v228, v120, v112, s[44:45]
	v_cndmask_b32_e64 v232, v117, 0, s[36:37]
	v_cndmask_b32_e64 v236, v117, 0, s[44:45]
	v_cndmask_b32_e64 v233, v125, v117, s[36:37]
	v_cndmask_b32_e64 v237, v125, v117, s[44:45]
	v_cndmask_b32_e64 v234, v113, v125, s[36:37]
	v_cndmask_b32_e64 v238, v113, v125, s[44:45]
	v_cndmask_b32_e64 v235, v121, v113, s[36:37]
	v_cndmask_b32_e64 v239, v121, v113, s[44:45]
	v_fma_f32 v204, v76, v116, v68
	v_fma_f32 v229, v76, v124, v68
	v_fma_f32 v230, v76, v112, v68
	v_fma_f32 v231, v76, v120, v68
	v_fma_f32 v205, v77, v117, v69
	v_fma_f32 v196, v77, v125, v69
	v_fma_f32 v197, v77, v113, v69
	v_fma_f32 v176, v77, v121, v69
	v_fmac_f32_dpp v204, v221, v72 row_ror:1 row_mask:0xf bank_mask:0xf
	v_fmac_f32_dpp v229, v222, v72 row_ror:1 row_mask:0xf bank_mask:0xf
	v_fmac_f32_dpp v230, v223, v72 row_ror:1 row_mask:0xf bank_mask:0xf
	v_fmac_f32_dpp v231, v224, v72 row_ror:1 row_mask:0xf bank_mask:0xf
	v_fmac_f32_dpp v205, v232, v73 row_ror:1 row_mask:0xf bank_mask:0xf
	v_fmac_f32_dpp v196, v233, v73 row_ror:1 row_mask:0xf bank_mask:0xf
	v_fmac_f32_dpp v197, v234, v73 row_ror:1 row_mask:0xf bank_mask:0xf
	v_fmac_f32_dpp v176, v235, v73 row_ror:1 row_mask:0xf bank_mask:0xf
	v_fmac_f32_dpp v204, v225, v64 row_ror:2 row_mask:0xf bank_mask:0xf
	v_fmac_f32_dpp v229, v226, v64 row_ror:2 row_mask:0xf bank_mask:0xf
	v_fmac_f32_dpp v230, v227, v64 row_ror:2 row_mask:0xf bank_mask:0xf
	v_fmac_f32_dpp v231, v228, v64 row_ror:2 row_mask:0xf bank_mask:0xf
	v_fmac_f32_dpp v205, v236, v65 row_ror:2 row_mask:0xf bank_mask:0xf
	v_fmac_f32_dpp v196, v237, v65 row_ror:2 row_mask:0xf bank_mask:0xf
	v_fmac_f32_dpp v197, v238, v65 row_ror:2 row_mask:0xf bank_mask:0xf
	v_fmac_f32_dpp v176, v239, v65 row_ror:2 row_mask:0xf bank_mask:0xf
	v_mul_f32_e32 v221, 0xbfb8aa3b, v204
	v_mul_f32_e32 v222, 0xbfb8aa3b, v229
	v_mul_f32_e32 v223, 0xbfb8aa3b, v230
	v_mul_f32_e32 v224, 0xbfb8aa3b, v231
	v_mul_f32_e32 v232, 0xbfb8aa3b, v205
	v_mul_f32_e32 v233, 0xbfb8aa3b, v196
	v_mul_f32_e32 v234, 0xbfb8aa3b, v197
	v_mul_f32_e32 v235, 0xbfb8aa3b, v176
	v_exp_f32_e32 v221, v221
	v_exp_f32_e32 v222, v222
	v_exp_f32_e32 v223, v223
	v_exp_f32_e32 v224, v224
	v_exp_f32_e32 v232, v232
	v_exp_f32_e32 v233, v233
	v_exp_f32_e32 v234, v234
	v_exp_f32_e32 v235, v235
	v_add_f32_e32 v221, 1.0, v221
	v_add_f32_e32 v222, 1.0, v222
	v_add_f32_e32 v223, 1.0, v223
	v_add_f32_e32 v224, 1.0, v224
	v_add_f32_e32 v232, 1.0, v232
	v_add_f32_e32 v233, 1.0, v233
	v_add_f32_e32 v234, 1.0, v234
	v_add_f32_e32 v235, 1.0, v235
	v_rcp_f32_e32 v221, v221
	v_rcp_f32_e32 v222, v222
	v_rcp_f32_e32 v223, v223
	v_rcp_f32_e32 v224, v224
	v_rcp_f32_e32 v232, v232
	v_rcp_f32_e32 v233, v233
	v_rcp_f32_e32 v234, v234
	v_rcp_f32_e32 v235, v235
	v_mul_f32_e32 v221, v204, v221
	v_mul_f32_e32 v222, v229, v222
	v_mul_f32_e32 v223, v230, v223
	v_mul_f32_e32 v224, v231, v224
	v_mul_f32_e32 v232, v205, v232
	v_mul_f32_e32 v233, v196, v233
	v_mul_f32_e32 v234, v197, v234
	v_mul_f32_e32 v235, v176, v235
	v_mul_f32_e32 v240, v108, v244
	v_mul_f32_e32 v104, v104, v245
	v_mul_f32_e32 v100, v100, v246
	v_mul_f32_e32 v96, v96, v247
	v_mul_f32_e32 v241, v109, v244
	v_mul_f32_e32 v105, v105, v245
	v_mul_f32_e32 v101, v101, v246
	v_mul_f32_e32 v97, v97, v247
	v_mul_f32_e32 v108, v221, v240
	v_mul_f32_e32 v104, v222, v104
	v_mul_f32_e32 v100, v223, v100
	v_mul_f32_e32 v96, v224, v96
	v_mul_f32_e32 v109, v232, v241
	v_mul_f32_e32 v105, v233, v105
	v_mul_f32_e32 v101, v234, v101
	v_mul_f32_e32 v97, v235, v97
	v_mul_f32_e32 v118, v118, v244
	v_mul_f32_e32 v126, v126, v245
	v_mul_f32_e32 v114, v114, v246
	v_mul_f32_e32 v122, v122, v247
	v_mul_f32_e32 v119, v119, v244
	v_mul_f32_e32 v127, v127, v245
	v_mul_f32_e32 v115, v115, v246
	v_mul_f32_e32 v123, v123, v247
	v_cndmask_b32_e64 v221, v118, 0, s[36:37]
	v_cndmask_b32_e64 v225, v118, 0, s[44:45]
	v_cndmask_b32_e64 v222, v126, v118, s[36:37]
	v_cndmask_b32_e64 v226, v126, v118, s[44:45]
	v_cndmask_b32_e64 v223, v114, v126, s[36:37]
	v_cndmask_b32_e64 v227, v114, v126, s[44:45]
	v_cndmask_b32_e64 v224, v122, v114, s[36:37]
	v_cndmask_b32_e64 v228, v122, v114, s[44:45]
	v_cndmask_b32_e64 v232, v119, 0, s[36:37]
	v_cndmask_b32_e64 v236, v119, 0, s[44:45]
	v_cndmask_b32_e64 v233, v127, v119, s[36:37]
	v_cndmask_b32_e64 v237, v127, v119, s[44:45]
	v_cndmask_b32_e64 v234, v115, v127, s[36:37]
	v_cndmask_b32_e64 v238, v115, v127, s[44:45]
	v_cndmask_b32_e64 v235, v123, v115, s[36:37]
	v_cndmask_b32_e64 v239, v123, v115, s[44:45]
	v_fma_f32 v206, v78, v118, v70
	v_fma_f32 v229, v78, v126, v70
	v_fma_f32 v230, v78, v114, v70
	v_fma_f32 v231, v78, v122, v70
	v_fma_f32 v207, v79, v119, v71
	v_fma_f32 v196, v79, v127, v71
	v_fma_f32 v197, v79, v115, v71
	v_fma_f32 v176, v79, v123, v71
	v_fmac_f32_dpp v206, v221, v74 row_ror:1 row_mask:0xf bank_mask:0xf
	v_fmac_f32_dpp v229, v222, v74 row_ror:1 row_mask:0xf bank_mask:0xf
	v_fmac_f32_dpp v230, v223, v74 row_ror:1 row_mask:0xf bank_mask:0xf
	v_fmac_f32_dpp v231, v224, v74 row_ror:1 row_mask:0xf bank_mask:0xf
	v_fmac_f32_dpp v207, v232, v75 row_ror:1 row_mask:0xf bank_mask:0xf
	v_fmac_f32_dpp v196, v233, v75 row_ror:1 row_mask:0xf bank_mask:0xf
	v_fmac_f32_dpp v197, v234, v75 row_ror:1 row_mask:0xf bank_mask:0xf
	v_fmac_f32_dpp v176, v235, v75 row_ror:1 row_mask:0xf bank_mask:0xf
	v_fmac_f32_dpp v206, v225, v66 row_ror:2 row_mask:0xf bank_mask:0xf
	v_fmac_f32_dpp v229, v226, v66 row_ror:2 row_mask:0xf bank_mask:0xf
	v_fmac_f32_dpp v230, v227, v66 row_ror:2 row_mask:0xf bank_mask:0xf
	v_fmac_f32_dpp v231, v228, v66 row_ror:2 row_mask:0xf bank_mask:0xf
	v_fmac_f32_dpp v207, v236, v67 row_ror:2 row_mask:0xf bank_mask:0xf
	v_fmac_f32_dpp v196, v237, v67 row_ror:2 row_mask:0xf bank_mask:0xf
	v_fmac_f32_dpp v197, v238, v67 row_ror:2 row_mask:0xf bank_mask:0xf
	v_fmac_f32_dpp v176, v239, v67 row_ror:2 row_mask:0xf bank_mask:0xf
	v_mul_f32_e32 v221, 0xbfb8aa3b, v206
	v_mul_f32_e32 v222, 0xbfb8aa3b, v229
	v_mul_f32_e32 v223, 0xbfb8aa3b, v230
	v_mul_f32_e32 v224, 0xbfb8aa3b, v231
	v_mul_f32_e32 v232, 0xbfb8aa3b, v207
	v_mul_f32_e32 v233, 0xbfb8aa3b, v196
	v_mul_f32_e32 v234, 0xbfb8aa3b, v197
	v_mul_f32_e32 v235, 0xbfb8aa3b, v176
	v_exp_f32_e32 v221, v221
	v_exp_f32_e32 v222, v222
	v_exp_f32_e32 v223, v223
	v_exp_f32_e32 v224, v224
	v_exp_f32_e32 v232, v232
	v_exp_f32_e32 v233, v233
	v_exp_f32_e32 v234, v234
	v_exp_f32_e32 v235, v235
	v_add_f32_e32 v221, 1.0, v221
	v_add_f32_e32 v222, 1.0, v222
	v_add_f32_e32 v223, 1.0, v223
	v_add_f32_e32 v224, 1.0, v224
	v_add_f32_e32 v232, 1.0, v232
	v_add_f32_e32 v233, 1.0, v233
	v_add_f32_e32 v234, 1.0, v234
	v_add_f32_e32 v235, 1.0, v235
	v_rcp_f32_e32 v221, v221
	v_rcp_f32_e32 v222, v222
	v_rcp_f32_e32 v223, v223
	v_rcp_f32_e32 v224, v224
	v_rcp_f32_e32 v232, v232
	v_rcp_f32_e32 v233, v233
	v_rcp_f32_e32 v234, v234
	v_rcp_f32_e32 v235, v235
	v_mul_f32_e32 v221, v206, v221
	v_mul_f32_e32 v222, v229, v222
	v_mul_f32_e32 v223, v230, v223
	v_mul_f32_e32 v224, v231, v224
	v_mul_f32_e32 v232, v207, v232
	v_mul_f32_e32 v233, v196, v233
	v_mul_f32_e32 v234, v197, v234
	v_mul_f32_e32 v235, v176, v235
	v_mul_f32_e32 v242, v110, v244
	v_mul_f32_e32 v106, v106, v245
	v_mul_f32_e32 v102, v102, v246
	v_mul_f32_e32 v98, v98, v247
	v_mul_f32_e32 v243, v111, v244
	v_mul_f32_e32 v107, v107, v245
	v_mul_f32_e32 v103, v103, v246
	v_mul_f32_e32 v99, v99, v247
	v_mul_f32_e32 v110, v221, v242
	v_mul_f32_e32 v106, v222, v106
	v_mul_f32_e32 v102, v223, v102
	v_mul_f32_e32 v98, v224, v98
	v_mul_f32_e32 v111, v232, v243
	v_mul_f32_e32 v107, v233, v107
	v_mul_f32_e32 v103, v234, v103
	v_mul_f32_e32 v99, v235, v99
	v_cvt_pk_bf16_f32 v140, v140, v141
	v_cvt_pk_bf16_f32 v141, v142, v143
	v_cvt_pk_bf16_f32 v142, v108, v109
	v_cvt_pk_bf16_f32 v143, v110, v111
	v_cvt_pk_bf16_f32 v136, v136, v137
	v_cvt_pk_bf16_f32 v137, v138, v139
	v_cvt_pk_bf16_f32 v138, v104, v105
	v_cvt_pk_bf16_f32 v139, v106, v107
	v_cvt_pk_bf16_f32 v132, v132, v133
	v_cvt_pk_bf16_f32 v133, v134, v135
	v_cvt_pk_bf16_f32 v134, v100, v101
	v_cvt_pk_bf16_f32 v135, v102, v103
	v_cvt_pk_bf16_f32 v128, v128, v129
	v_cvt_pk_bf16_f32 v129, v130, v131
	v_cvt_pk_bf16_f32 v130, v96, v97
	v_cvt_pk_bf16_f32 v131, v98, v99
	v_or_b32_e32 v170, s11, v216
	v_mad_i64_i32 v[170:171], vcc, v170, s10, 0
	v_lshlrev_b64 v[170:171], 2, v[170:171]
	v_lshl_add_u64 v[170:171], v[170:171], 0, v[190:191]
	v_lshl_add_u64 v[172:173], s[50:51], 0, v[170:171]
	v_lshl_add_u64 v[170:171], s[92:93], 0, v[170:171]
	s_and_saveexec_b64 s[0:1], s[42:43]
	global_store_dwordx4 v[172:173], v[200:203], off
	global_store_dwordx4 v[172:173], v[204:207], off offset:16
	global_store_dwordx4 v[170:171], v[192:195], off
	global_store_dwordx4 v[170:171], v[240:243], off offset:16
	s_or_b64 exec, exec, s[0:1]
	v_add_u32_e32 v170, s11, v218
	v_mad_i64_i32 v[170:171], vcc, v170, s10, 0
	v_lshlrev_b64 v[170:171], 2, v[170:171]
	v_lshl_add_u64 v[170:171], s[52:53], 0, v[170:171]
	v_lshl_add_u64 v[170:171], v[188:189], 2, v[170:171]
	s_and_saveexec_b64 s[0:1], s[44:45]
	global_store_dwordx4 v[170:171], v[150:153], off
	global_store_dwordx4 v[170:171], v[120:123], off offset:16
	s_or_b64 exec, exec, s[0:1]
	v_mov_b64_e32 v[170:171], s[94:95]
	v_mad_i64_i32 v[170:171], vcc, v198, s20, v[170:171]
	v_lshl_add_u64 v[170:171], v[188:189], 1, v[170:171]
	s_and_saveexec_b64 s[0:1], s[40:41]
	global_store_dwordx4 v[170:171], v[140:143], off
	s_or_b64 exec, exec, s[0:1]
	v_or_b32_e32 v172, 16, v198
	v_mov_b64_e32 v[170:171], s[94:95]
	v_mad_i64_i32 v[170:171], vcc, v172, s20, v[170:171]
	v_lshl_add_u64 v[170:171], v[188:189], 1, v[170:171]
	global_store_dwordx4 v[170:171], v[136:139], off
	v_or_b32_e32 v172, 32, v198
	v_mov_b64_e32 v[170:171], s[94:95]
	v_mad_i64_i32 v[170:171], vcc, v172, s20, v[170:171]
	v_lshl_add_u64 v[170:171], v[188:189], 1, v[170:171]
	global_store_dwordx4 v[170:171], v[132:135], off
	v_or_b32_e32 v172, 48, v198
	v_mov_b64_e32 v[170:171], s[94:95]
	v_mad_i64_i32 v[170:171], vcc, v172, s20, v[170:171]
	v_lshl_add_u64 v[170:171], v[188:189], 1, v[170:171]
	global_store_dwordx4 v[170:171], v[128:131], off
	s_add_i32 s11, s11, 4
	v_mul_f32_e32 v48, v48, v248
	v_mul_f32_e32 v60, v60, v249
	v_mul_f32_e32 v56, v56, v250
	v_mul_f32_e32 v52, v52, v251
	v_mul_f32_e32 v49, v49, v248
	v_mul_f32_e32 v61, v61, v249
	v_mul_f32_e32 v57, v57, v250
	v_mul_f32_e32 v53, v53, v251
	v_cndmask_b32_e64 v221, v48, 0, s[36:37]
	v_cndmask_b32_e64 v225, v48, 0, s[44:45]
	v_cndmask_b32_e64 v222, v60, v48, s[36:37]
	v_cndmask_b32_e64 v226, v60, v48, s[44:45]
	v_cndmask_b32_e64 v223, v56, v60, s[36:37]
	v_cndmask_b32_e64 v227, v56, v60, s[44:45]
	v_cndmask_b32_e64 v224, v52, v56, s[36:37]
	v_cndmask_b32_e64 v228, v52, v56, s[44:45]
	v_cndmask_b32_e64 v232, v49, 0, s[36:37]
	v_cndmask_b32_e64 v236, v49, 0, s[44:45]
	v_cndmask_b32_e64 v233, v61, v49, s[36:37]
	v_cndmask_b32_e64 v237, v61, v49, s[44:45]
	v_cndmask_b32_e64 v234, v57, v61, s[36:37]
	v_cndmask_b32_e64 v238, v57, v61, s[44:45]
	v_cndmask_b32_e64 v235, v53, v57, s[36:37]
	v_cndmask_b32_e64 v239, v53, v57, s[44:45]
	v_fma_f32 v200, v92, v48, v84
	v_fma_f32 v229, v92, v60, v84
	v_fma_f32 v230, v92, v56, v84
	v_fma_f32 v231, v92, v52, v84
	v_fma_f32 v201, v93, v49, v85
	v_fma_f32 v196, v93, v61, v85
	v_fma_f32 v197, v93, v57, v85
	v_fma_f32 v176, v93, v53, v85
	v_fmac_f32_dpp v200, v221, v88 row_ror:1 row_mask:0xf bank_mask:0xf
	v_fmac_f32_dpp v229, v222, v88 row_ror:1 row_mask:0xf bank_mask:0xf
	v_fmac_f32_dpp v230, v223, v88 row_ror:1 row_mask:0xf bank_mask:0xf
	v_fmac_f32_dpp v231, v224, v88 row_ror:1 row_mask:0xf bank_mask:0xf
	v_fmac_f32_dpp v201, v232, v89 row_ror:1 row_mask:0xf bank_mask:0xf
	v_fmac_f32_dpp v196, v233, v89 row_ror:1 row_mask:0xf bank_mask:0xf
	v_fmac_f32_dpp v197, v234, v89 row_ror:1 row_mask:0xf bank_mask:0xf
	v_fmac_f32_dpp v176, v235, v89 row_ror:1 row_mask:0xf bank_mask:0xf
	v_fmac_f32_dpp v200, v225, v80 row_ror:2 row_mask:0xf bank_mask:0xf
	v_fmac_f32_dpp v229, v226, v80 row_ror:2 row_mask:0xf bank_mask:0xf
	v_fmac_f32_dpp v230, v227, v80 row_ror:2 row_mask:0xf bank_mask:0xf
	v_fmac_f32_dpp v231, v228, v80 row_ror:2 row_mask:0xf bank_mask:0xf
	v_fmac_f32_dpp v201, v236, v81 row_ror:2 row_mask:0xf bank_mask:0xf
	v_fmac_f32_dpp v196, v237, v81 row_ror:2 row_mask:0xf bank_mask:0xf
	v_fmac_f32_dpp v197, v238, v81 row_ror:2 row_mask:0xf bank_mask:0xf
	v_fmac_f32_dpp v176, v239, v81 row_ror:2 row_mask:0xf bank_mask:0xf
	v_mul_f32_e32 v221, 0xbfb8aa3b, v200
	v_mul_f32_e32 v222, 0xbfb8aa3b, v229
	v_mul_f32_e32 v223, 0xbfb8aa3b, v230
	v_mul_f32_e32 v224, 0xbfb8aa3b, v231
	v_mul_f32_e32 v232, 0xbfb8aa3b, v201
	v_mul_f32_e32 v233, 0xbfb8aa3b, v196
	v_mul_f32_e32 v234, 0xbfb8aa3b, v197
	v_mul_f32_e32 v235, 0xbfb8aa3b, v176
	v_exp_f32_e32 v221, v221
	v_exp_f32_e32 v222, v222
	v_exp_f32_e32 v223, v223
	v_exp_f32_e32 v224, v224
	v_exp_f32_e32 v232, v232
	v_exp_f32_e32 v233, v233
	v_exp_f32_e32 v234, v234
	v_exp_f32_e32 v235, v235
	v_add_f32_e32 v221, 1.0, v221
	v_add_f32_e32 v222, 1.0, v222
	v_add_f32_e32 v223, 1.0, v223
	v_add_f32_e32 v224, 1.0, v224
	v_add_f32_e32 v232, 1.0, v232
	v_add_f32_e32 v233, 1.0, v233
	v_add_f32_e32 v234, 1.0, v234
	v_add_f32_e32 v235, 1.0, v235
	v_rcp_f32_e32 v221, v221
	v_rcp_f32_e32 v222, v222
	v_rcp_f32_e32 v223, v223
	v_rcp_f32_e32 v224, v224
	v_rcp_f32_e32 v232, v232
	v_rcp_f32_e32 v233, v233
	v_rcp_f32_e32 v234, v234
	v_rcp_f32_e32 v235, v235
	v_mul_f32_e32 v221, v200, v221
	v_mul_f32_e32 v222, v229, v222
	v_mul_f32_e32 v223, v230, v223
	v_mul_f32_e32 v224, v231, v224
	v_mul_f32_e32 v232, v201, v232
	v_mul_f32_e32 v233, v196, v233
	v_mul_f32_e32 v234, v197, v234
	v_mul_f32_e32 v235, v176, v235
	v_mul_f32_e32 v192, v44, v248
	v_mul_f32_e32 v40, v40, v249
	v_mul_f32_e32 v36, v36, v250
	v_mul_f32_e32 v32, v32, v251
	v_mul_f32_e32 v193, v45, v248
	v_mul_f32_e32 v41, v41, v249
	v_mul_f32_e32 v37, v37, v250
	v_mul_f32_e32 v33, v33, v251
	v_mul_f32_e32 v44, v221, v192
	v_mul_f32_e32 v40, v222, v40
	v_mul_f32_e32 v36, v223, v36
	v_mul_f32_e32 v32, v224, v32
	v_mul_f32_e32 v45, v232, v193
	v_mul_f32_e32 v41, v233, v41
	v_mul_f32_e32 v37, v234, v37
	v_mul_f32_e32 v33, v235, v33
	v_mul_f32_e32 v50, v50, v248
	v_mul_f32_e32 v62, v62, v249
	v_mul_f32_e32 v58, v58, v250
	v_mul_f32_e32 v54, v54, v251
	v_mul_f32_e32 v51, v51, v248
	v_mul_f32_e32 v63, v63, v249
	v_mul_f32_e32 v59, v59, v250
	v_mul_f32_e32 v55, v55, v251
	v_cndmask_b32_e64 v221, v50, 0, s[36:37]
	v_cndmask_b32_e64 v225, v50, 0, s[44:45]
	v_cndmask_b32_e64 v222, v62, v50, s[36:37]
	v_cndmask_b32_e64 v226, v62, v50, s[44:45]
	v_cndmask_b32_e64 v223, v58, v62, s[36:37]
	v_cndmask_b32_e64 v227, v58, v62, s[44:45]
	v_cndmask_b32_e64 v224, v54, v58, s[36:37]
	v_cndmask_b32_e64 v228, v54, v58, s[44:45]
	v_cndmask_b32_e64 v232, v51, 0, s[36:37]
	v_cndmask_b32_e64 v236, v51, 0, s[44:45]
	v_cndmask_b32_e64 v233, v63, v51, s[36:37]
	v_cndmask_b32_e64 v237, v63, v51, s[44:45]
	v_cndmask_b32_e64 v234, v59, v63, s[36:37]
	v_cndmask_b32_e64 v238, v59, v63, s[44:45]
	v_cndmask_b32_e64 v235, v55, v59, s[36:37]
	v_cndmask_b32_e64 v239, v55, v59, s[44:45]
	v_fma_f32 v202, v94, v50, v86
	v_fma_f32 v229, v94, v62, v86
	v_fma_f32 v230, v94, v58, v86
	v_fma_f32 v231, v94, v54, v86
	v_fma_f32 v203, v95, v51, v87
	v_fma_f32 v196, v95, v63, v87
	v_fma_f32 v197, v95, v59, v87
	v_fma_f32 v176, v95, v55, v87
	v_fmac_f32_dpp v202, v221, v90 row_ror:1 row_mask:0xf bank_mask:0xf
	v_fmac_f32_dpp v229, v222, v90 row_ror:1 row_mask:0xf bank_mask:0xf
	v_fmac_f32_dpp v230, v223, v90 row_ror:1 row_mask:0xf bank_mask:0xf
	v_fmac_f32_dpp v231, v224, v90 row_ror:1 row_mask:0xf bank_mask:0xf
	v_fmac_f32_dpp v203, v232, v91 row_ror:1 row_mask:0xf bank_mask:0xf
	v_fmac_f32_dpp v196, v233, v91 row_ror:1 row_mask:0xf bank_mask:0xf
	v_fmac_f32_dpp v197, v234, v91 row_ror:1 row_mask:0xf bank_mask:0xf
	v_fmac_f32_dpp v176, v235, v91 row_ror:1 row_mask:0xf bank_mask:0xf
	v_fmac_f32_dpp v202, v225, v82 row_ror:2 row_mask:0xf bank_mask:0xf
	v_fmac_f32_dpp v229, v226, v82 row_ror:2 row_mask:0xf bank_mask:0xf
	v_fmac_f32_dpp v230, v227, v82 row_ror:2 row_mask:0xf bank_mask:0xf
	v_fmac_f32_dpp v231, v228, v82 row_ror:2 row_mask:0xf bank_mask:0xf
	v_fmac_f32_dpp v203, v236, v83 row_ror:2 row_mask:0xf bank_mask:0xf
	v_fmac_f32_dpp v196, v237, v83 row_ror:2 row_mask:0xf bank_mask:0xf
	v_fmac_f32_dpp v197, v238, v83 row_ror:2 row_mask:0xf bank_mask:0xf
	v_fmac_f32_dpp v176, v239, v83 row_ror:2 row_mask:0xf bank_mask:0xf
	v_mul_f32_e32 v221, 0xbfb8aa3b, v202
	v_mul_f32_e32 v222, 0xbfb8aa3b, v229
	v_mul_f32_e32 v223, 0xbfb8aa3b, v230
	v_mul_f32_e32 v224, 0xbfb8aa3b, v231
	v_mul_f32_e32 v232, 0xbfb8aa3b, v203
	v_mul_f32_e32 v233, 0xbfb8aa3b, v196
	v_mul_f32_e32 v234, 0xbfb8aa3b, v197
	v_mul_f32_e32 v235, 0xbfb8aa3b, v176
	v_exp_f32_e32 v221, v221
	v_exp_f32_e32 v222, v222
	v_exp_f32_e32 v223, v223
	v_exp_f32_e32 v224, v224
	v_exp_f32_e32 v232, v232
	v_exp_f32_e32 v233, v233
	v_exp_f32_e32 v234, v234
	v_exp_f32_e32 v235, v235
	v_add_f32_e32 v221, 1.0, v221
	v_add_f32_e32 v222, 1.0, v222
	v_add_f32_e32 v223, 1.0, v223
	v_add_f32_e32 v224, 1.0, v224
	v_add_f32_e32 v232, 1.0, v232
	v_add_f32_e32 v233, 1.0, v233
	v_add_f32_e32 v234, 1.0, v234
	v_add_f32_e32 v235, 1.0, v235
	v_rcp_f32_e32 v221, v221
	v_rcp_f32_e32 v222, v222
	v_rcp_f32_e32 v223, v223
	v_rcp_f32_e32 v224, v224
	v_rcp_f32_e32 v232, v232
	v_rcp_f32_e32 v233, v233
	v_rcp_f32_e32 v234, v234
	v_rcp_f32_e32 v235, v235
	v_mul_f32_e32 v221, v202, v221
	v_mul_f32_e32 v222, v229, v222
	v_mul_f32_e32 v223, v230, v223
	v_mul_f32_e32 v224, v231, v224
	v_mul_f32_e32 v232, v203, v232
	v_mul_f32_e32 v233, v196, v233
	v_mul_f32_e32 v234, v197, v234
	v_mul_f32_e32 v235, v176, v235
	v_mul_f32_e32 v194, v46, v248
	v_mul_f32_e32 v42, v42, v249
	v_mul_f32_e32 v38, v38, v250
	v_mul_f32_e32 v34, v34, v251
	v_mul_f32_e32 v195, v47, v248
	v_mul_f32_e32 v43, v43, v249
	v_mul_f32_e32 v39, v39, v250
	v_mul_f32_e32 v35, v35, v251
	v_mul_f32_e32 v46, v221, v194
	v_mul_f32_e32 v42, v222, v42
	v_mul_f32_e32 v38, v223, v38
	v_mul_f32_e32 v34, v224, v34
	v_mul_f32_e32 v47, v232, v195
	v_mul_f32_e32 v43, v233, v43
	v_mul_f32_e32 v39, v234, v39
	v_mul_f32_e32 v35, v235, v35
	v_mul_f32_e32 v20, v20, v248
	v_mul_f32_e32 v28, v28, v249
	v_mul_f32_e32 v16, v16, v250
	v_mul_f32_e32 v24, v24, v251
	v_mul_f32_e32 v21, v21, v248
	v_mul_f32_e32 v29, v29, v249
	v_mul_f32_e32 v17, v17, v250
	v_mul_f32_e32 v25, v25, v251
	v_cndmask_b32_e64 v221, v20, 0, s[36:37]
	v_cndmask_b32_e64 v225, v20, 0, s[44:45]
	v_cndmask_b32_e64 v222, v28, v20, s[36:37]
	v_cndmask_b32_e64 v226, v28, v20, s[44:45]
	v_cndmask_b32_e64 v223, v16, v28, s[36:37]
	v_cndmask_b32_e64 v227, v16, v28, s[44:45]
	v_cndmask_b32_e64 v224, v24, v16, s[36:37]
	v_cndmask_b32_e64 v228, v24, v16, s[44:45]
	v_cndmask_b32_e64 v232, v21, 0, s[36:37]
	v_cndmask_b32_e64 v236, v21, 0, s[44:45]
	v_cndmask_b32_e64 v233, v29, v21, s[36:37]
	v_cndmask_b32_e64 v237, v29, v21, s[44:45]
	v_cndmask_b32_e64 v234, v17, v29, s[36:37]
	v_cndmask_b32_e64 v238, v17, v29, s[44:45]
	v_cndmask_b32_e64 v235, v25, v17, s[36:37]
	v_cndmask_b32_e64 v239, v25, v17, s[44:45]
	v_fma_f32 v204, v76, v20, v68
	v_fma_f32 v229, v76, v28, v68
	v_fma_f32 v230, v76, v16, v68
	v_fma_f32 v231, v76, v24, v68
	v_fma_f32 v205, v77, v21, v69
	v_fma_f32 v196, v77, v29, v69
	v_fma_f32 v197, v77, v17, v69
	v_fma_f32 v176, v77, v25, v69
	v_fmac_f32_dpp v204, v221, v72 row_ror:1 row_mask:0xf bank_mask:0xf
	v_fmac_f32_dpp v229, v222, v72 row_ror:1 row_mask:0xf bank_mask:0xf
	v_fmac_f32_dpp v230, v223, v72 row_ror:1 row_mask:0xf bank_mask:0xf
	v_fmac_f32_dpp v231, v224, v72 row_ror:1 row_mask:0xf bank_mask:0xf
	v_fmac_f32_dpp v205, v232, v73 row_ror:1 row_mask:0xf bank_mask:0xf
	v_fmac_f32_dpp v196, v233, v73 row_ror:1 row_mask:0xf bank_mask:0xf
	v_fmac_f32_dpp v197, v234, v73 row_ror:1 row_mask:0xf bank_mask:0xf
	v_fmac_f32_dpp v176, v235, v73 row_ror:1 row_mask:0xf bank_mask:0xf
	v_fmac_f32_dpp v204, v225, v64 row_ror:2 row_mask:0xf bank_mask:0xf
	v_fmac_f32_dpp v229, v226, v64 row_ror:2 row_mask:0xf bank_mask:0xf
	v_fmac_f32_dpp v230, v227, v64 row_ror:2 row_mask:0xf bank_mask:0xf
	v_fmac_f32_dpp v231, v228, v64 row_ror:2 row_mask:0xf bank_mask:0xf
	v_fmac_f32_dpp v205, v236, v65 row_ror:2 row_mask:0xf bank_mask:0xf
	v_fmac_f32_dpp v196, v237, v65 row_ror:2 row_mask:0xf bank_mask:0xf
	v_fmac_f32_dpp v197, v238, v65 row_ror:2 row_mask:0xf bank_mask:0xf
	v_fmac_f32_dpp v176, v239, v65 row_ror:2 row_mask:0xf bank_mask:0xf
	v_mul_f32_e32 v221, 0xbfb8aa3b, v204
	v_mul_f32_e32 v222, 0xbfb8aa3b, v229
	v_mul_f32_e32 v223, 0xbfb8aa3b, v230
	v_mul_f32_e32 v224, 0xbfb8aa3b, v231
	v_mul_f32_e32 v232, 0xbfb8aa3b, v205
	v_mul_f32_e32 v233, 0xbfb8aa3b, v196
	v_mul_f32_e32 v234, 0xbfb8aa3b, v197
	v_mul_f32_e32 v235, 0xbfb8aa3b, v176
	v_exp_f32_e32 v221, v221
	v_exp_f32_e32 v222, v222
	v_exp_f32_e32 v223, v223
	v_exp_f32_e32 v224, v224
	v_exp_f32_e32 v232, v232
	v_exp_f32_e32 v233, v233
	v_exp_f32_e32 v234, v234
	v_exp_f32_e32 v235, v235
	v_add_f32_e32 v221, 1.0, v221
	v_add_f32_e32 v222, 1.0, v222
	v_add_f32_e32 v223, 1.0, v223
	v_add_f32_e32 v224, 1.0, v224
	v_add_f32_e32 v232, 1.0, v232
	v_add_f32_e32 v233, 1.0, v233
	v_add_f32_e32 v234, 1.0, v234
	v_add_f32_e32 v235, 1.0, v235
	v_rcp_f32_e32 v221, v221
	v_rcp_f32_e32 v222, v222
	v_rcp_f32_e32 v223, v223
	v_rcp_f32_e32 v224, v224
	v_rcp_f32_e32 v232, v232
	v_rcp_f32_e32 v233, v233
	v_rcp_f32_e32 v234, v234
	v_rcp_f32_e32 v235, v235
	v_mul_f32_e32 v221, v204, v221
	v_mul_f32_e32 v222, v229, v222
	v_mul_f32_e32 v223, v230, v223
	v_mul_f32_e32 v224, v231, v224
	v_mul_f32_e32 v232, v205, v232
	v_mul_f32_e32 v233, v196, v233
	v_mul_f32_e32 v234, v197, v234
	v_mul_f32_e32 v235, v176, v235
	v_mul_f32_e32 v240, v12, v248
	v_mul_f32_e32 v8, v8, v249
	v_mul_f32_e32 v4, v4, v250
	v_mul_f32_e32 v0, v0, v251
	v_mul_f32_e32 v241, v13, v248
	v_mul_f32_e32 v9, v9, v249
	v_mul_f32_e32 v5, v5, v250
	v_mul_f32_e32 v1, v1, v251
	v_mul_f32_e32 v12, v221, v240
	v_mul_f32_e32 v8, v222, v8
	v_mul_f32_e32 v4, v223, v4
	v_mul_f32_e32 v0, v224, v0
	v_mul_f32_e32 v13, v232, v241
	v_mul_f32_e32 v9, v233, v9
	v_mul_f32_e32 v5, v234, v5
	v_mul_f32_e32 v1, v235, v1
	v_mul_f32_e32 v22, v22, v248
	v_mul_f32_e32 v30, v30, v249
	v_mul_f32_e32 v18, v18, v250
	v_mul_f32_e32 v26, v26, v251
	v_mul_f32_e32 v23, v23, v248
	v_mul_f32_e32 v31, v31, v249
	v_mul_f32_e32 v19, v19, v250
	v_mul_f32_e32 v27, v27, v251
	v_cndmask_b32_e64 v221, v22, 0, s[36:37]
	v_cndmask_b32_e64 v225, v22, 0, s[44:45]
	v_cndmask_b32_e64 v222, v30, v22, s[36:37]
	v_cndmask_b32_e64 v226, v30, v22, s[44:45]
	v_cndmask_b32_e64 v223, v18, v30, s[36:37]
	v_cndmask_b32_e64 v227, v18, v30, s[44:45]
	v_cndmask_b32_e64 v224, v26, v18, s[36:37]
	v_cndmask_b32_e64 v228, v26, v18, s[44:45]
	v_cndmask_b32_e64 v232, v23, 0, s[36:37]
	v_cndmask_b32_e64 v236, v23, 0, s[44:45]
	v_cndmask_b32_e64 v233, v31, v23, s[36:37]
	v_cndmask_b32_e64 v237, v31, v23, s[44:45]
	v_cndmask_b32_e64 v234, v19, v31, s[36:37]
	v_cndmask_b32_e64 v238, v19, v31, s[44:45]
	v_cndmask_b32_e64 v235, v27, v19, s[36:37]
	v_cndmask_b32_e64 v239, v27, v19, s[44:45]
	v_fma_f32 v206, v78, v22, v70
	v_fma_f32 v229, v78, v30, v70
	v_fma_f32 v230, v78, v18, v70
	v_fma_f32 v231, v78, v26, v70
	v_fma_f32 v207, v79, v23, v71
	v_fma_f32 v196, v79, v31, v71
	v_fma_f32 v197, v79, v19, v71
	v_fma_f32 v176, v79, v27, v71
	v_fmac_f32_dpp v206, v221, v74 row_ror:1 row_mask:0xf bank_mask:0xf
	v_fmac_f32_dpp v229, v222, v74 row_ror:1 row_mask:0xf bank_mask:0xf
	v_fmac_f32_dpp v230, v223, v74 row_ror:1 row_mask:0xf bank_mask:0xf
	v_fmac_f32_dpp v231, v224, v74 row_ror:1 row_mask:0xf bank_mask:0xf
	v_fmac_f32_dpp v207, v232, v75 row_ror:1 row_mask:0xf bank_mask:0xf
	v_fmac_f32_dpp v196, v233, v75 row_ror:1 row_mask:0xf bank_mask:0xf
	v_fmac_f32_dpp v197, v234, v75 row_ror:1 row_mask:0xf bank_mask:0xf
	v_fmac_f32_dpp v176, v235, v75 row_ror:1 row_mask:0xf bank_mask:0xf
	v_fmac_f32_dpp v206, v225, v66 row_ror:2 row_mask:0xf bank_mask:0xf
	v_fmac_f32_dpp v229, v226, v66 row_ror:2 row_mask:0xf bank_mask:0xf
	v_fmac_f32_dpp v230, v227, v66 row_ror:2 row_mask:0xf bank_mask:0xf
	v_fmac_f32_dpp v231, v228, v66 row_ror:2 row_mask:0xf bank_mask:0xf
	v_fmac_f32_dpp v207, v236, v67 row_ror:2 row_mask:0xf bank_mask:0xf
	v_fmac_f32_dpp v196, v237, v67 row_ror:2 row_mask:0xf bank_mask:0xf
	v_fmac_f32_dpp v197, v238, v67 row_ror:2 row_mask:0xf bank_mask:0xf
	v_fmac_f32_dpp v176, v239, v67 row_ror:2 row_mask:0xf bank_mask:0xf
	v_mul_f32_e32 v221, 0xbfb8aa3b, v206
	v_mul_f32_e32 v222, 0xbfb8aa3b, v229
	v_mul_f32_e32 v223, 0xbfb8aa3b, v230
	v_mul_f32_e32 v224, 0xbfb8aa3b, v231
	v_mul_f32_e32 v232, 0xbfb8aa3b, v207
	v_mul_f32_e32 v233, 0xbfb8aa3b, v196
	v_mul_f32_e32 v234, 0xbfb8aa3b, v197
	v_mul_f32_e32 v235, 0xbfb8aa3b, v176
	v_exp_f32_e32 v221, v221
	v_exp_f32_e32 v222, v222
	v_exp_f32_e32 v223, v223
	v_exp_f32_e32 v224, v224
	v_exp_f32_e32 v232, v232
	v_exp_f32_e32 v233, v233
	v_exp_f32_e32 v234, v234
	v_exp_f32_e32 v235, v235
	v_add_f32_e32 v221, 1.0, v221
	v_add_f32_e32 v222, 1.0, v222
	v_add_f32_e32 v223, 1.0, v223
	v_add_f32_e32 v224, 1.0, v224
	v_add_f32_e32 v232, 1.0, v232
	v_add_f32_e32 v233, 1.0, v233
	v_add_f32_e32 v234, 1.0, v234
	v_add_f32_e32 v235, 1.0, v235
	v_rcp_f32_e32 v221, v221
	v_rcp_f32_e32 v222, v222
	v_rcp_f32_e32 v223, v223
	v_rcp_f32_e32 v224, v224
	v_rcp_f32_e32 v232, v232
	v_rcp_f32_e32 v233, v233
	v_rcp_f32_e32 v234, v234
	v_rcp_f32_e32 v235, v235
	v_mul_f32_e32 v221, v206, v221
	v_mul_f32_e32 v222, v229, v222
	v_mul_f32_e32 v223, v230, v223
	v_mul_f32_e32 v224, v231, v224
	v_mul_f32_e32 v232, v207, v232
	v_mul_f32_e32 v233, v196, v233
	v_mul_f32_e32 v234, v197, v234
	v_mul_f32_e32 v235, v176, v235
	v_mul_f32_e32 v242, v14, v248
	v_mul_f32_e32 v10, v10, v249
	v_mul_f32_e32 v6, v6, v250
	v_mul_f32_e32 v2, v2, v251
	v_mul_f32_e32 v243, v15, v248
	v_mul_f32_e32 v11, v11, v249
	v_mul_f32_e32 v7, v7, v250
	v_mul_f32_e32 v3, v3, v251
	v_mul_f32_e32 v14, v221, v242
	v_mul_f32_e32 v10, v222, v10
	v_mul_f32_e32 v6, v223, v6
	v_mul_f32_e32 v2, v224, v2
	v_mul_f32_e32 v15, v232, v243
	v_mul_f32_e32 v11, v233, v11
	v_mul_f32_e32 v7, v234, v7
	v_mul_f32_e32 v3, v235, v3
	v_cvt_pk_bf16_f32 v44, v44, v45
	v_cvt_pk_bf16_f32 v45, v46, v47
	v_cvt_pk_bf16_f32 v46, v12, v13
	v_cvt_pk_bf16_f32 v47, v14, v15
	v_cvt_pk_bf16_f32 v40, v40, v41
	v_cvt_pk_bf16_f32 v41, v42, v43
	v_cvt_pk_bf16_f32 v42, v8, v9
	v_cvt_pk_bf16_f32 v43, v10, v11
	v_cvt_pk_bf16_f32 v36, v36, v37
	v_cvt_pk_bf16_f32 v37, v38, v39
	v_cvt_pk_bf16_f32 v38, v4, v5
	v_cvt_pk_bf16_f32 v39, v6, v7
	v_cvt_pk_bf16_f32 v32, v32, v33
	v_cvt_pk_bf16_f32 v33, v34, v35
	v_cvt_pk_bf16_f32 v34, v0, v1
	v_cvt_pk_bf16_f32 v35, v2, v3
	v_or_b32_e32 v170, s11, v216
	v_mad_i64_i32 v[170:171], vcc, v170, s10, 0
	v_lshlrev_b64 v[170:171], 2, v[170:171]
	v_lshl_add_u64 v[170:171], v[170:171], 0, v[190:191]
	v_lshl_add_u64 v[172:173], s[50:51], 0, v[170:171]
	v_lshl_add_u64 v[170:171], s[92:93], 0, v[170:171]
	s_and_saveexec_b64 s[0:1], s[42:43]
	global_store_dwordx4 v[172:173], v[200:203], off
	global_store_dwordx4 v[172:173], v[204:207], off offset:16
	global_store_dwordx4 v[170:171], v[192:195], off
	global_store_dwordx4 v[170:171], v[240:243], off offset:16
	s_or_b64 exec, exec, s[0:1]
	v_add_u32_e32 v170, s11, v218
	v_mad_i64_i32 v[170:171], vcc, v170, s10, 0
	v_lshlrev_b64 v[170:171], 2, v[170:171]
	v_lshl_add_u64 v[170:171], s[52:53], 0, v[170:171]
	v_lshl_add_u64 v[170:171], v[188:189], 2, v[170:171]
	s_and_saveexec_b64 s[0:1], s[44:45]
	global_store_dwordx4 v[170:171], v[52:55], off
	global_store_dwordx4 v[170:171], v[24:27], off offset:16
	s_or_b64 exec, exec, s[0:1]
	v_mov_b64_e32 v[170:171], s[94:95]
	v_mad_i64_i32 v[170:171], vcc, v168, s20, v[170:171]
	v_lshl_add_u64 v[170:171], v[188:189], 1, v[170:171]
	s_and_saveexec_b64 s[0:1], s[40:41]
	global_store_dwordx4 v[170:171], v[44:47], off
	s_or_b64 exec, exec, s[0:1]
	v_or_b32_e32 v172, 16, v168
	v_mov_b64_e32 v[170:171], s[94:95]
	v_mad_i64_i32 v[170:171], vcc, v172, s20, v[170:171]
	v_lshl_add_u64 v[170:171], v[188:189], 1, v[170:171]
	global_store_dwordx4 v[170:171], v[40:43], off
	v_or_b32_e32 v172, 32, v168
	v_mov_b64_e32 v[170:171], s[94:95]
	v_mad_i64_i32 v[170:171], vcc, v172, s20, v[170:171]
	v_lshl_add_u64 v[170:171], v[188:189], 1, v[170:171]
	global_store_dwordx4 v[170:171], v[36:39], off
	v_or_b32_e32 v172, 48, v168
	v_mov_b64_e32 v[170:171], s[94:95]
	v_mad_i64_i32 v[170:171], vcc, v172, s20, v[170:171]
	v_lshl_add_u64 v[170:171], v[188:189], 1, v[170:171]
	global_store_dwordx4 v[170:171], v[32:35], off
	s_and_b64 vcc, exec, s[46:47]
	s_mov_b32 s0, s76
	s_mov_b32 s84, s78
	s_mov_b64 s[82:83], s[72:73]
	s_mov_b64 s[86:87], s[80:81]
	s_cbranch_vccnz .LBB0_146
	s_branch .LBB0_122
